# P5 K-loop: fragment ds_reads issued last in the load stage, lgkmcnt wait moved behind the barrier (on top of c2)
# speedup vs baseline: 1.0002x; 1.0002x over previous
.LBB0_872:
	s_add_i32 s77, s52, 2
	s_add_u32 s50, s34, 0xfffc0080
	s_addc_u32 s51, s35, -1
	s_cmp_eq_u32 s70, s52
	s_cselect_b32 s52, s30, s21
	s_cselect_b32 s55, s29, s51
	s_cselect_b32 s54, s28, s50
	s_cselect_b32 s53, s31, s23
	v_lshl_add_u64 v[214:215], s[34:35], 0, v[132:133]
	s_add_i32 m0, s60, 0xc000
	s_nop 0
	global_load_lds_dwordx4 v[214:215], off
	v_lshl_add_u64 v[214:215], s[34:35], 0, v[134:135]
	s_add_i32 m0, s60, 0xe000
	s_nop 0
	global_load_lds_dwordx4 v[214:215], off
	s_waitcnt vmcnt(8)
	v_add_u32_e32 v162, s73, v140
	v_add_u32_e32 v178, s74, v140
	ds_read_b128 v[150:153], v162
	ds_read_b128 v[154:157], v162 offset:1024
	ds_read_b128 v[158:161], v162 offset:2048
	ds_read_b128 v[162:165], v162 offset:3072
	ds_read_b128 v[166:169], v178
	ds_read_b128 v[170:173], v178 offset:1024
	ds_read_b128 v[174:177], v178 offset:2048
	ds_read_b128 v[178:181], v178 offset:3072
	ds_read_b128 v[182:185], v149
	ds_read_b128 v[186:189], v149 offset:1024
	ds_read_b128 v[190:193], v149 offset:2048
	ds_read_b128 v[194:197], v149 offset:3072
	ds_read_b128 v[198:201], v149 offset:4096
	ds_read_b128 v[202:205], v149 offset:5120
	ds_read_b128 v[206:209], v149 offset:6144
	ds_read_b128 v[210:213], v149 offset:7168
	s_barrier
	s_waitcnt lgkmcnt(0)
	v_mfma_f32_16x16x32_bf16 v[78:81], v[150:153], v[182:185], v[78:81]
	v_mfma_f32_16x16x32_bf16 v[14:17], v[158:161], v[182:185], v[14:17]
	v_mfma_f32_16x16x32_bf16 v[66:69], v[150:153], v[190:193], v[66:69]
	v_mfma_f32_16x16x32_bf16 v[2:5], v[158:161], v[190:193], v[2:5]
	v_mfma_f32_16x16x32_bf16 v[70:73], v[150:153], v[198:201], v[70:73]
	v_mfma_f32_16x16x32_bf16 v[6:9], v[158:161], v[198:201], v[6:9]
	v_mfma_f32_16x16x32_bf16 v[74:77], v[150:153], v[206:209], v[74:77]
	v_mfma_f32_16x16x32_bf16 v[10:13], v[158:161], v[206:209], v[10:13]
	v_mfma_f32_16x16x32_bf16 v[78:81], v[154:157], v[186:189], v[78:81]
	v_mfma_f32_16x16x32_bf16 v[14:17], v[162:165], v[186:189], v[14:17]
	v_mfma_f32_16x16x32_bf16 v[66:69], v[154:157], v[194:197], v[66:69]
	v_mfma_f32_16x16x32_bf16 v[2:5], v[162:165], v[194:197], v[2:5]
	v_mfma_f32_16x16x32_bf16 v[70:73], v[154:157], v[202:205], v[70:73]
	v_mfma_f32_16x16x32_bf16 v[6:9], v[162:165], v[202:205], v[6:9]
	v_mfma_f32_16x16x32_bf16 v[74:77], v[154:157], v[210:213], v[74:77]
	v_mfma_f32_16x16x32_bf16 v[10:13], v[162:165], v[210:213], v[10:13]
	v_mfma_f32_16x16x32_bf16 v[98:101], v[166:169], v[182:185], v[98:101]
	v_mfma_f32_16x16x32_bf16 v[34:37], v[174:177], v[182:185], v[34:37]
	v_mfma_f32_16x16x32_bf16 v[82:85], v[166:169], v[190:193], v[82:85]
	v_mfma_f32_16x16x32_bf16 v[18:21], v[174:177], v[190:193], v[18:21]
	v_mfma_f32_16x16x32_bf16 v[86:89], v[166:169], v[198:201], v[86:89]
	v_mfma_f32_16x16x32_bf16 v[22:25], v[174:177], v[198:201], v[22:25]
	v_mfma_f32_16x16x32_bf16 v[94:97], v[166:169], v[206:209], v[94:97]
	v_mfma_f32_16x16x32_bf16 v[30:33], v[174:177], v[206:209], v[30:33]
	v_mfma_f32_16x16x32_bf16 v[98:101], v[170:173], v[186:189], v[98:101]
	v_mfma_f32_16x16x32_bf16 v[34:37], v[178:181], v[186:189], v[34:37]
	v_mfma_f32_16x16x32_bf16 v[82:85], v[170:173], v[194:197], v[82:85]
	v_mfma_f32_16x16x32_bf16 v[18:21], v[178:181], v[194:197], v[18:21]
	v_mfma_f32_16x16x32_bf16 v[86:89], v[170:173], v[202:205], v[86:89]
	v_mfma_f32_16x16x32_bf16 v[22:25], v[178:181], v[202:205], v[22:25]
	v_mfma_f32_16x16x32_bf16 v[94:97], v[170:173], v[210:213], v[94:97]
	v_mfma_f32_16x16x32_bf16 v[30:33], v[178:181], v[210:213], v[30:33]
	s_barrier
	s_add_i32 s50, s73, s15
	v_lshl_add_u64 v[214:215], s[52:53], 0, v[228:229]
	s_mov_b32 m0, s50
	s_nop 0
	global_load_lds_dwordx4 v[214:215], off
	s_add_i32 m0, s50, 0x2000
	s_add_u32 s50, s52, 0x40000
	v_lshl_add_u64 v[216:217], s[52:53], 0, v[232:233]
	s_addc_u32 s51, s53, 0
	s_add_i32 s78, s74, s15
	global_load_lds_dwordx4 v[216:217], off
	v_lshl_add_u64 v[218:219], s[50:51], 0, v[228:229]
	s_mov_b32 m0, s78
	v_lshl_add_u64 v[220:221], s[54:55], 0, v[230:231]
	global_load_lds_dwordx4 v[218:219], off
	v_lshl_add_u64 v[218:219], s[50:51], 0, v[232:233]
	s_add_i32 m0, s78, 0x2000
	s_nop 0
	global_load_lds_dwordx4 v[218:219], off
	v_lshl_add_u64 v[218:219], s[54:55], 0, v[226:227]
	s_mov_b32 m0, s60
	s_nop 0
	global_load_lds_dwordx4 v[218:219], off
	s_mov_b32 m0, s61
	s_nop 0
	global_load_lds_dwordx4 v[220:221], off
	s_waitcnt vmcnt(8)
	ds_read_b128 v[182:185], v149 offset:16384
	ds_read_b128 v[186:189], v149 offset:17408
	ds_read_b128 v[190:193], v149 offset:18432
	ds_read_b128 v[194:197], v149 offset:19456
	ds_read_b128 v[198:201], v149 offset:20480
	ds_read_b128 v[202:205], v149 offset:21504
	ds_read_b128 v[206:209], v149 offset:22528
	ds_read_b128 v[210:213], v149 offset:23552
	s_barrier
	s_waitcnt lgkmcnt(0)
	v_mfma_f32_16x16x32_bf16 v[90:93], v[150:153], v[182:185], v[90:93]
	v_mfma_f32_16x16x32_bf16 v[26:29], v[158:161], v[182:185], v[26:29]
	v_mfma_f32_16x16x32_bf16 v[102:105], v[150:153], v[190:193], v[102:105]
	v_mfma_f32_16x16x32_bf16 v[38:41], v[158:161], v[190:193], v[38:41]
	v_mfma_f32_16x16x32_bf16 v[106:109], v[150:153], v[198:201], v[106:109]
	v_mfma_f32_16x16x32_bf16 v[42:45], v[158:161], v[198:201], v[42:45]
	v_mfma_f32_16x16x32_bf16 v[110:113], v[150:153], v[206:209], v[110:113]
	v_mfma_f32_16x16x32_bf16 v[46:49], v[158:161], v[206:209], v[46:49]
	v_mfma_f32_16x16x32_bf16 v[90:93], v[154:157], v[186:189], v[90:93]
	v_mfma_f32_16x16x32_bf16 v[26:29], v[162:165], v[186:189], v[26:29]
	v_mfma_f32_16x16x32_bf16 v[102:105], v[154:157], v[194:197], v[102:105]
	v_mfma_f32_16x16x32_bf16 v[38:41], v[162:165], v[194:197], v[38:41]
	v_mfma_f32_16x16x32_bf16 v[106:109], v[154:157], v[202:205], v[106:109]
	v_mfma_f32_16x16x32_bf16 v[42:45], v[162:165], v[202:205], v[42:45]
	v_mfma_f32_16x16x32_bf16 v[110:113], v[154:157], v[210:213], v[110:113]
	v_mfma_f32_16x16x32_bf16 v[46:49], v[162:165], v[210:213], v[46:49]
	v_mfma_f32_16x16x32_bf16 v[114:117], v[166:169], v[182:185], v[114:117]
	v_mfma_f32_16x16x32_bf16 v[50:53], v[174:177], v[182:185], v[50:53]
	v_mfma_f32_16x16x32_bf16 v[118:121], v[166:169], v[190:193], v[118:121]
	v_mfma_f32_16x16x32_bf16 v[54:57], v[174:177], v[190:193], v[54:57]
	v_mfma_f32_16x16x32_bf16 v[122:125], v[166:169], v[198:201], v[122:125]
	v_mfma_f32_16x16x32_bf16 v[58:61], v[174:177], v[198:201], v[58:61]
	v_mfma_f32_16x16x32_bf16 v[126:129], v[166:169], v[206:209], v[126:129]
	v_mfma_f32_16x16x32_bf16 v[62:65], v[174:177], v[206:209], v[62:65]
	v_mfma_f32_16x16x32_bf16 v[114:117], v[170:173], v[186:189], v[114:117]
	v_mfma_f32_16x16x32_bf16 v[50:53], v[178:181], v[186:189], v[50:53]
	v_mfma_f32_16x16x32_bf16 v[118:121], v[170:173], v[194:197], v[118:121]
	v_mfma_f32_16x16x32_bf16 v[54:57], v[178:181], v[194:197], v[54:57]
	v_mfma_f32_16x16x32_bf16 v[122:125], v[170:173], v[202:205], v[122:125]
	v_mfma_f32_16x16x32_bf16 v[58:61], v[178:181], v[202:205], v[58:61]
	v_mfma_f32_16x16x32_bf16 v[126:129], v[170:173], v[210:213], v[126:129]
	v_mfma_f32_16x16x32_bf16 v[62:65], v[178:181], v[210:213], v[62:65]
	s_barrier
	s_add_u32 s50, s54, 0x40000
	s_addc_u32 s51, s55, 0
	s_mov_b32 m0, s62
	v_lshl_add_u64 v[222:223], s[50:51], 0, v[226:227]
	global_load_lds_dwordx4 v[222:223], off
	v_lshl_add_u64 v[222:223], s[50:51], 0, v[230:231]
	s_mov_b32 m0, s63
	s_nop 0
	global_load_lds_dwordx4 v[222:223], off
	s_waitcnt vmcnt(8)
	s_add_i32 s78, 0, 0x18000
	s_add_i32 s79, 0, 0x1c000
	v_add_u32_e32 v162, s78, v140
	v_add_u32_e32 v178, s79, v140
	ds_read_b128 v[150:153], v162
	ds_read_b128 v[154:157], v162 offset:1024
	ds_read_b128 v[158:161], v162 offset:2048
	ds_read_b128 v[162:165], v162 offset:3072
	ds_read_b128 v[166:169], v178
	ds_read_b128 v[170:173], v178 offset:1024
	ds_read_b128 v[174:177], v178 offset:2048
	ds_read_b128 v[178:181], v178 offset:3072
	ds_read_b128 v[182:185], v149 offset:32768
	ds_read_b128 v[186:189], v149 offset:33792
	ds_read_b128 v[190:193], v149 offset:34816
	ds_read_b128 v[194:197], v149 offset:35840
	ds_read_b128 v[198:201], v149 offset:36864
	ds_read_b128 v[202:205], v149 offset:37888
	ds_read_b128 v[206:209], v149 offset:38912
	ds_read_b128 v[210:213], v149 offset:39936
	s_barrier
	s_waitcnt lgkmcnt(0)
	v_mfma_f32_16x16x32_bf16 v[78:81], v[150:153], v[182:185], v[78:81]
	v_mfma_f32_16x16x32_bf16 v[14:17], v[158:161], v[182:185], v[14:17]
	v_mfma_f32_16x16x32_bf16 v[66:69], v[150:153], v[190:193], v[66:69]
	v_mfma_f32_16x16x32_bf16 v[2:5], v[158:161], v[190:193], v[2:5]
	v_mfma_f32_16x16x32_bf16 v[70:73], v[150:153], v[198:201], v[70:73]
	v_mfma_f32_16x16x32_bf16 v[6:9], v[158:161], v[198:201], v[6:9]
	v_mfma_f32_16x16x32_bf16 v[74:77], v[150:153], v[206:209], v[74:77]
	v_mfma_f32_16x16x32_bf16 v[10:13], v[158:161], v[206:209], v[10:13]
	v_mfma_f32_16x16x32_bf16 v[78:81], v[154:157], v[186:189], v[78:81]
	v_mfma_f32_16x16x32_bf16 v[14:17], v[162:165], v[186:189], v[14:17]
	v_mfma_f32_16x16x32_bf16 v[66:69], v[154:157], v[194:197], v[66:69]
	v_mfma_f32_16x16x32_bf16 v[2:5], v[162:165], v[194:197], v[2:5]
	v_mfma_f32_16x16x32_bf16 v[70:73], v[154:157], v[202:205], v[70:73]
	v_mfma_f32_16x16x32_bf16 v[6:9], v[162:165], v[202:205], v[6:9]
	v_mfma_f32_16x16x32_bf16 v[74:77], v[154:157], v[210:213], v[74:77]
	v_mfma_f32_16x16x32_bf16 v[10:13], v[162:165], v[210:213], v[10:13]
	v_mfma_f32_16x16x32_bf16 v[98:101], v[166:169], v[182:185], v[98:101]
	v_mfma_f32_16x16x32_bf16 v[34:37], v[174:177], v[182:185], v[34:37]
	v_mfma_f32_16x16x32_bf16 v[82:85], v[166:169], v[190:193], v[82:85]
	v_mfma_f32_16x16x32_bf16 v[18:21], v[174:177], v[190:193], v[18:21]
	v_mfma_f32_16x16x32_bf16 v[86:89], v[166:169], v[198:201], v[86:89]
	v_mfma_f32_16x16x32_bf16 v[22:25], v[174:177], v[198:201], v[22:25]
	v_mfma_f32_16x16x32_bf16 v[94:97], v[166:169], v[206:209], v[94:97]
	v_mfma_f32_16x16x32_bf16 v[30:33], v[174:177], v[206:209], v[30:33]
	v_mfma_f32_16x16x32_bf16 v[98:101], v[170:173], v[186:189], v[98:101]
	v_mfma_f32_16x16x32_bf16 v[34:37], v[178:181], v[186:189], v[34:37]
	v_mfma_f32_16x16x32_bf16 v[82:85], v[170:173], v[194:197], v[82:85]
	v_mfma_f32_16x16x32_bf16 v[18:21], v[178:181], v[194:197], v[18:21]
	v_mfma_f32_16x16x32_bf16 v[86:89], v[170:173], v[202:205], v[86:89]
	v_mfma_f32_16x16x32_bf16 v[22:25], v[178:181], v[202:205], v[22:25]
	v_mfma_f32_16x16x32_bf16 v[94:97], v[170:173], v[210:213], v[94:97]
	v_mfma_f32_16x16x32_bf16 v[30:33], v[178:181], v[210:213], v[30:33]
	s_barrier
	s_add_i32 s50, s78, s15
	v_lshl_add_u64 v[214:215], v[214:215], 0, s[8:9]
	s_mov_b32 m0, s50
	s_nop 0
	global_load_lds_dwordx4 v[214:215], off
	s_add_i32 m0, s50, 0x2000
	s_add_u32 s50, s52, 0x40080
	v_lshl_add_u64 v[214:215], v[216:217], 0, s[8:9]
	s_addc_u32 s51, s53, 0
	s_add_i32 s52, s79, s15
	global_load_lds_dwordx4 v[214:215], off
	v_lshl_add_u64 v[214:215], s[50:51], 0, v[228:229]
	s_mov_b32 m0, s52
	s_nop 0
	global_load_lds_dwordx4 v[214:215], off
	v_lshl_add_u64 v[214:215], s[50:51], 0, v[232:233]
	s_add_i32 m0, s52, 0x2000
	s_nop 0
	global_load_lds_dwordx4 v[214:215], off
	v_lshl_add_u64 v[214:215], v[218:219], 0, s[8:9]
	s_mov_b32 m0, s68
	s_nop 0
	global_load_lds_dwordx4 v[214:215], off
	v_lshl_add_u64 v[214:215], v[220:221], 0, s[8:9]
	s_mov_b32 m0, s69
	s_nop 0
	global_load_lds_dwordx4 v[214:215], off
	s_waitcnt vmcnt(8)
	ds_read_b128 v[182:185], v149 offset:49152
	ds_read_b128 v[186:189], v149 offset:50176
	ds_read_b128 v[190:193], v149 offset:51200
	ds_read_b128 v[194:197], v149 offset:52224
	ds_read_b128 v[198:201], v149 offset:53248
	ds_read_b128 v[202:205], v149 offset:54272
	ds_read_b128 v[206:209], v149 offset:55296
	ds_read_b128 v[210:213], v149 offset:56320
	s_barrier
	s_waitcnt lgkmcnt(0)
	v_mfma_f32_16x16x32_bf16 v[90:93], v[150:153], v[182:185], v[90:93]
	v_mfma_f32_16x16x32_bf16 v[26:29], v[158:161], v[182:185], v[26:29]
	v_mfma_f32_16x16x32_bf16 v[102:105], v[150:153], v[190:193], v[102:105]
	v_mfma_f32_16x16x32_bf16 v[38:41], v[158:161], v[190:193], v[38:41]
	v_mfma_f32_16x16x32_bf16 v[106:109], v[150:153], v[198:201], v[106:109]
	v_mfma_f32_16x16x32_bf16 v[42:45], v[158:161], v[198:201], v[42:45]
	v_mfma_f32_16x16x32_bf16 v[110:113], v[150:153], v[206:209], v[110:113]
	v_mfma_f32_16x16x32_bf16 v[46:49], v[158:161], v[206:209], v[46:49]
	v_mfma_f32_16x16x32_bf16 v[90:93], v[154:157], v[186:189], v[90:93]
	v_mfma_f32_16x16x32_bf16 v[26:29], v[162:165], v[186:189], v[26:29]
	v_mfma_f32_16x16x32_bf16 v[102:105], v[154:157], v[194:197], v[102:105]
	v_mfma_f32_16x16x32_bf16 v[38:41], v[162:165], v[194:197], v[38:41]
	v_mfma_f32_16x16x32_bf16 v[106:109], v[154:157], v[202:205], v[106:109]
	v_mfma_f32_16x16x32_bf16 v[42:45], v[162:165], v[202:205], v[42:45]
	v_mfma_f32_16x16x32_bf16 v[110:113], v[154:157], v[210:213], v[110:113]
	v_mfma_f32_16x16x32_bf16 v[46:49], v[162:165], v[210:213], v[46:49]
	v_mfma_f32_16x16x32_bf16 v[114:117], v[166:169], v[182:185], v[114:117]
	v_mfma_f32_16x16x32_bf16 v[50:53], v[174:177], v[182:185], v[50:53]
	v_mfma_f32_16x16x32_bf16 v[118:121], v[166:169], v[190:193], v[118:121]
	v_mfma_f32_16x16x32_bf16 v[54:57], v[174:177], v[190:193], v[54:57]
	v_mfma_f32_16x16x32_bf16 v[122:125], v[166:169], v[198:201], v[122:125]
	v_mfma_f32_16x16x32_bf16 v[58:61], v[174:177], v[198:201], v[58:61]
	v_mfma_f32_16x16x32_bf16 v[126:129], v[166:169], v[206:209], v[126:129]
	v_mfma_f32_16x16x32_bf16 v[62:65], v[174:177], v[206:209], v[62:65]
	v_mfma_f32_16x16x32_bf16 v[114:117], v[170:173], v[186:189], v[114:117]
	v_mfma_f32_16x16x32_bf16 v[50:53], v[178:181], v[186:189], v[50:53]
	v_mfma_f32_16x16x32_bf16 v[118:121], v[170:173], v[194:197], v[118:121]
	v_mfma_f32_16x16x32_bf16 v[54:57], v[178:181], v[194:197], v[54:57]
	v_mfma_f32_16x16x32_bf16 v[122:125], v[170:173], v[202:205], v[122:125]
	v_mfma_f32_16x16x32_bf16 v[58:61], v[178:181], v[202:205], v[58:61]
	v_mfma_f32_16x16x32_bf16 v[126:129], v[170:173], v[210:213], v[126:129]
	v_mfma_f32_16x16x32_bf16 v[62:65], v[178:181], v[210:213], v[62:65]
	s_barrier
	s_add_u32 s34, s34, 0x100
	s_addc_u32 s35, s35, 0
	s_add_u32 s21, s21, 0x100
	s_addc_u32 s23, s23, 0
	s_cmp_ge_i32 s77, s66
	s_mov_b32 s52, s77
	s_cbranch_scc0 .LBB0_872
